# grid barrier: non-leader WGs sleep ~1us before their first poll of the global counter (less polling traffic while the XCD leaders release)
# speedup vs baseline: 1.0032x; 1.0022x over previous
; __device__ __forceinline__ unsigned xb_ld(unsigned* p)              { return __hip_atomic_load(p, __ATOMIC_RELAXED, __HIP_MEMORY_SCOPE_AGENT); }
; __device__ __forceinline__ unsigned xb_add(unsigned* p, unsigned v) { return __hip_atomic_fetch_add(p, v, __ATOMIC_RELAXED, __HIP_MEMORY_SCOPE_AGENT); }
; #define XB_SPIN(cond, bar) do { unsigned _sp = 0; while (cond) { __builtin_amdgcn_s_sleep(1); \
;     if ((++_sp & 255u) == 0u) { if (xb_ld(&(bar)[XB_TMO])) break; if (_sp > XB_SPIN_CAP) { atomicAdd(&(bar)[XB_TMO], 1u); break; } } } } while (0)
; __device__ __forceinline__ void xcd_barrier(const XcdBarrier& b) {
;     ...
;         const unsigned old = xb_add(&bar[XB_XSUB(b.x)], 1u);
;         const unsigned gen = old / nloc;
;         if (old + 1u == (gen + 1u) * nloc) {
;             __builtin_amdgcn_fence(__ATOMIC_RELEASE, "agent");
;             asm volatile("s_waitcnt vmcnt(0)" ::: "memory");
;             const unsigned og = xb_add(&bar[XB_TOP], 1u);
;             const unsigned tg = og / nx;
;             if (og + 1u == (tg + 1u) * nx) xb_add(&bar[XB_TOPGEN], 1u);
;             else XB_SPIN(xb_ld(&bar[XB_TOPGEN]) == tg, bar);
;             __builtin_amdgcn_fence(__ATOMIC_ACQUIRE, "agent");
;             xb_add(&bar[XB_XGEN(b.x)], 1u);
;             asm volatile("s_waitcnt vmcnt(0)" ::: "memory");
;         } else {
;             XB_SPIN(xb_ld(&bar[XB_XGEN(b.x)]) == gen, bar);
;             __builtin_amdgcn_fence(__ATOMIC_ACQUIRE, "agent");
;             asm volatile("s_waitcnt vmcnt(0)" ::: "memory");
.Lxb0_have:
	s_mov_b64 exec, 1
	v_readlane_b32 s99, v252, 2
	s_lshl_b32 s99, s99, 8
	s_add_u32 s99, s99, 0x1400
	v_mov_b32_e32 v254, s99
	v_mov_b32_e32 v255, 1
	global_atomic_add v255, v254, v255, s[68:69] sc0
	v_readlane_b32 s99, v253, 2
	s_add_u32 s99, s99, 1
	v_writelane_b32 v253, s99, 2
	s_mul_i32 s98, s98, s99
	s_waitcnt vmcnt(0)
	v_readfirstlane_b32 vcc_lo, v255
	s_add_u32 vcc_lo, vcc_lo, 1
	s_cmp_lg_u32 vcc_lo, s98
	s_cbranch_scc1 .Lxb0_wait
	buffer_wbl2 sc1
	s_waitcnt vmcnt(0)
	v_mov_b32_e32 v254, 0x3400
	v_mov_b32_e32 v255, 1
	global_atomic_add v254, v255, s[68:69]
	s_branch .Lxb0_wait2
.Lxb0_wait:
	s_sleep 32
